# scan1 tail: second item's row loads hoisted behind the first item's loads, first item's store drain folded into the chunk-end drain
# baseline (speedup 1.0000x reference)
.LBB0_506:
	s_or_b64 exec, exec, s[0:1]
	s_waitcnt lgkmcnt(0)
	s_barrier
	ds_read_b32 v0, v44
	s_movk_i32 s0, 0x213
	s_waitcnt lgkmcnt(0)
	v_cmp_lt_u32_e32 vcc, s0, v0
	v_readfirstlane_b32 s8, v0
	s_mov_b64 s[0:1], -1
	s_cbranch_vccnz .LBB0_471
	v_mov_b32_e32 v46, v153
	s_lshr_b32 s33, s8, 1
	s_lshl_b32 s0, s8, 9
	s_and_b32 s36, s0, 0x200
	v_lshlrev_b32_e32 v0, 3, v46
	v_ashrrev_i32_e32 v47, 5, v46
	v_and_b32_e32 v48, 0xf8, v0
	s_lshl_b32 s37, s33, 6
	v_or_b32_e32 v45, s36, v48
	v_lshl_add_u32 v42, v47, 2, s37
	v_lshlrev_b32_e32 v40, 1, v45
	v_ashrrev_i32_e32 v43, 31, v42
	v_lshl_add_u64 v[0:1], s[20:21], 0, v[40:41]
	v_lshl_add_u64 v[2:3], s[34:35], 0, v[40:41]
	v_lshlrev_b64 v[4:5], 11, v[42:43]
	v_lshl_add_u64 v[6:7], v[0:1], 0, v[4:5]
	v_lshl_add_u64 v[4:5], v[2:3], 0, v[4:5]
	v_mov_b32_e32 v232, v6
	v_mov_b32_e32 v233, v7
	global_load_dwordx4 v[36:39], v[6:7], off
	v_mov_b32_e32 v234, v4
	v_mov_b32_e32 v235, v5
	global_load_dwordx4 v[32:35], v[4:5], off
	v_or_b32_e32 v4, 1, v42
	v_ashrrev_i32_e32 v5, 31, v4
	v_lshlrev_b64 v[4:5], 11, v[4:5]
	v_lshl_add_u64 v[6:7], v[0:1], 0, v[4:5]
	v_lshl_add_u64 v[4:5], v[2:3], 0, v[4:5]
	v_mov_b32_e32 v236, v6
	v_mov_b32_e32 v237, v7
	global_load_dwordx4 v[28:31], v[6:7], off
	v_mov_b32_e32 v238, v4
	v_mov_b32_e32 v239, v5
	global_load_dwordx4 v[20:23], v[4:5], off
	v_or_b32_e32 v4, 2, v42
	v_ashrrev_i32_e32 v5, 31, v4
	v_lshlrev_b64 v[4:5], 11, v[4:5]
	v_lshl_add_u64 v[6:7], v[0:1], 0, v[4:5]
	v_lshl_add_u64 v[8:9], v[2:3], 0, v[4:5]
	v_mov_b32_e32 v240, v6
	v_mov_b32_e32 v241, v7
	global_load_dwordx4 v[4:7], v[6:7], off
	s_nop 0
	v_mov_b32_e32 v242, v8
	v_mov_b32_e32 v243, v9
	global_load_dwordx4 v[24:27], v[8:9], off
	v_or_b32_e32 v8, 3, v42
	v_ashrrev_i32_e32 v9, 31, v8
	v_lshlrev_b64 v[8:9], 11, v[8:9]
	v_lshl_add_u64 v[0:1], v[0:1], 0, v[8:9]
	v_lshl_add_u64 v[2:3], v[2:3], 0, v[8:9]
	v_mov_b32_e32 v244, v0
	v_mov_b32_e32 v245, v1
	global_load_dwordx4 v[16:19], v[0:1], off
	v_mov_b32_e32 v246, v2
	v_mov_b32_e32 v247, v3
	global_load_dwordx4 v[8:11], v[2:3], off
	v_cmp_lt_i32_e32 vcc, s27, v42
	v_mov_b32_e32 v3, 0
	v_mov_b32_e32 v2, 0
	v_mov_b32_e32 v1, 0
	v_mov_b32_e32 v0, 0
	v_mov_b32_e32 v15, 0
	v_mov_b32_e32 v14, 0
	v_mov_b32_e32 v13, 0
	v_mov_b32_e32 v12, 0
	s_and_saveexec_b64 s[0:1], vcc
	s_cbranch_execz .LBB0_509
	v_add_u32_e32 v0, 0xffffbf80, v42
	v_lshrrev_b32_e32 v40, 2, v0
	v_lshlrev_b64 v[0:1], 12, v[40:41]
	v_lshl_add_u64 v[0:1], s[58:59], 0, v[0:1]
	v_lshlrev_b32_e32 v40, 2, v45
	v_lshl_add_u64 v[0:1], v[0:1], 0, v[40:41]
	global_load_dwordx4 v[12:15], v[0:1], off
	s_nop 0
	global_load_dwordx4 v[0:3], v[0:1], off offset:16
.LBB0_509:
	s_or_b64 exec, exec, s[0:1]
	global_load_dwordx4 v[200:203], v[232:233], off offset:512
	global_load_dwordx4 v[204:207], v[234:235], off offset:512
	global_load_dwordx4 v[208:211], v[236:237], off offset:512
	global_load_dwordx4 v[212:215], v[238:239], off offset:512
	global_load_dwordx4 v[216:219], v[240:241], off offset:512
	global_load_dwordx4 v[220:223], v[242:243], off offset:512
	global_load_dwordx4 v[224:227], v[244:245], off offset:512
	global_load_dwordx4 v[228:231], v[246:247], off offset:512
	s_waitcnt vmcnt(15)
	v_lshlrev_b32_e32 v40, 16, v36
	v_and_b32_e32 v36, 0xffff0000, v36
	v_sub_f32_e32 v43, 1.0, v36
	v_lshlrev_b32_e32 v36, 16, v37
	v_sub_f32_e32 v49, 1.0, v36
	v_and_b32_e32 v36, 0xffff0000, v37
	s_waitcnt vmcnt(12)
	v_lshlrev_b32_e32 v71, 16, v20
	v_and_b32_e32 v72, 0xffff0000, v20
	v_lshlrev_b32_e32 v73, 16, v21
	v_and_b32_e32 v74, 0xffff0000, v21
	s_waitcnt vmcnt(9)
	v_lshlrev_b32_e32 v21, 16, v16
	v_lshlrev_b32_e32 v20, 16, v4
	v_sub_f32_e32 v50, 1.0, v36
	v_lshlrev_b32_e32 v36, 16, v38
	v_lshlrev_b32_e32 v78, 16, v24
	v_and_b32_e32 v79, 0xffff0000, v24
	v_lshlrev_b32_e32 v80, 16, v25
	v_and_b32_e32 v81, 0xffff0000, v25
	v_pk_add_f32 v[24:25], v[20:21], 1.0 op_sel_hi:[1,0] neg_lo:[1,0] neg_hi:[1,0]
	v_and_b32_e32 v21, 0xffff0000, v16
	v_and_b32_e32 v20, 0xffff0000, v4
	v_sub_f32_e32 v51, 1.0, v36
	v_and_b32_e32 v36, 0xffff0000, v38
	v_lshlrev_b32_e32 v55, 16, v32
	v_and_b32_e32 v56, 0xffff0000, v32
	v_lshlrev_b32_e32 v32, 16, v28
	v_lshlrev_b32_e32 v82, 16, v26
	v_and_b32_e32 v83, 0xffff0000, v26
	v_lshlrev_b32_e32 v84, 16, v27
	v_and_b32_e32 v85, 0xffff0000, v27
	v_pk_add_f32 v[26:27], v[20:21], 1.0 op_sel_hi:[1,0] neg_lo:[1,0] neg_hi:[1,0]
	v_lshlrev_b32_e32 v20, 16, v5
	v_and_b32_e32 v16, 0xffff0000, v5
	v_lshlrev_b32_e32 v5, 16, v18
	v_lshlrev_b32_e32 v4, 16, v6
	v_sub_f32_e32 v52, 1.0, v36
	v_lshlrev_b32_e32 v36, 16, v39
	v_lshlrev_b32_e32 v57, 16, v33
	v_and_b32_e32 v58, 0xffff0000, v33
	v_sub_f32_e32 v63, 1.0, v32
	v_pk_add_f32 v[32:33], v[4:5], 1.0 op_sel_hi:[1,0] neg_lo:[1,0] neg_hi:[1,0]
	v_and_b32_e32 v5, 0xffff0000, v18
	v_and_b32_e32 v4, 0xffff0000, v6
	v_sub_f32_e32 v53, 1.0, v36
	v_and_b32_e32 v36, 0xffff0000, v39
	v_lshlrev_b32_e32 v59, 16, v34
	v_and_b32_e32 v60, 0xffff0000, v34
	v_lshlrev_b32_e32 v61, 16, v35
	v_and_b32_e32 v62, 0xffff0000, v35
	v_pk_add_f32 v[34:35], v[4:5], 1.0 op_sel_hi:[1,0] neg_lo:[1,0] neg_hi:[1,0]
	v_lshlrev_b32_e32 v5, 16, v19
	v_lshlrev_b32_e32 v4, 16, v7
	v_sub_f32_e32 v54, 1.0, v36
	v_pk_add_f32 v[36:37], v[4:5], 1.0 op_sel_hi:[1,0] neg_lo:[1,0] neg_hi:[1,0]
	v_and_b32_e32 v5, 0xffff0000, v19
	v_and_b32_e32 v4, 0xffff0000, v7
	v_pk_add_f32 v[38:39], v[4:5], 1.0 op_sel_hi:[1,0] neg_lo:[1,0] neg_hi:[1,0]
	v_mul_lo_u32 v4, v42, s28
	v_add_u32_e32 v4, 0xfe03f0, v4
	v_and_b32_e32 v28, 0xffff0000, v28
	v_alignbit_b32 v4, v4, v4, 4
	v_sub_f32_e32 v64, 1.0, v28
	v_lshlrev_b32_e32 v28, 16, v29
	v_cmp_gt_u32_e64 s[0:1], s29, v4
	v_sub_f32_e32 v65, 1.0, v28
	v_and_b32_e32 v28, 0xffff0000, v29
	s_or_b64 vcc, vcc, s[0:1]
	v_sub_f32_e32 v66, 1.0, v28
	v_lshlrev_b32_e32 v28, 16, v30
	s_waitcnt vmcnt(8)
	v_cndmask_b32_e32 v0, 0, v0, vcc
	v_sub_f32_e32 v67, 1.0, v28
	v_and_b32_e32 v28, 0xffff0000, v30
	v_fmac_f32_e32 v59, v51, v0
	v_cndmask_b32_e32 v0, 0, v1, vcc
	v_sub_f32_e32 v40, 1.0, v40
	v_sub_f32_e32 v68, 1.0, v28
	v_lshlrev_b32_e32 v28, 16, v31
	v_cndmask_b32_e32 v4, 0, v12, vcc
	v_fmac_f32_e32 v60, v52, v0
	v_cndmask_b32_e32 v0, 0, v2, vcc
	v_sub_f32_e32 v69, 1.0, v28
	v_and_b32_e32 v28, 0xffff0000, v31
	v_lshlrev_b32_e32 v21, 16, v17
	v_fmac_f32_e32 v55, v40, v4
	v_cndmask_b32_e32 v4, 0, v13, vcc
	v_fmac_f32_e32 v61, v53, v0
	v_cndmask_b32_e32 v0, 0, v3, vcc
	v_sub_f32_e32 v70, 1.0, v28
	v_lshlrev_b32_e32 v76, 16, v23
	v_and_b32_e32 v77, 0xffff0000, v23
	v_pk_add_f32 v[28:29], v[20:21], 1.0 op_sel_hi:[1,0] neg_lo:[1,0] neg_hi:[1,0]
	v_lshlrev_b32_e32 v21, 16, v10
	v_and_b32_e32 v23, 0xffff0000, v10
	v_fmac_f32_e32 v56, v43, v4
	v_cndmask_b32_e32 v4, 0, v14, vcc
	v_cndmask_b32_e64 v10, v49, 0, vcc
	v_cndmask_b32_e64 v1, v51, 0, vcc
	v_fmac_f32_e32 v62, v54, v0
	v_cndmask_b32_e64 v0, v54, 0, vcc
	v_lshlrev_b32_e32 v5, 16, v8
	v_and_b32_e32 v7, 0xffff0000, v8
	v_cndmask_b32_e64 v6, v40, 0, vcc
	v_cndmask_b32_e64 v8, v43, 0, vcc
	v_fmac_f32_e32 v57, v49, v4
	v_cndmask_b32_e32 v4, 0, v15, vcc
	v_mul_f32_e32 v10, v10, v65
	v_mul_f32_e32 v1, v1, v67
	v_mul_f32_e32 v0, v0, v70
	v_lshlrev_b32_e32 v75, 16, v22
	v_and_b32_e32 v22, 0xffff0000, v22
	v_and_b32_e32 v17, 0xffff0000, v17
	v_fmac_f32_e32 v58, v50, v4
	v_cndmask_b32_e64 v4, v50, 0, vcc
	v_cndmask_b32_e64 v2, v52, 0, vcc
	v_cndmask_b32_e64 v3, v53, 0, vcc
	v_fmac_f32_e32 v71, v63, v55
	v_mul_f32_e32 v6, v6, v63
	v_fmac_f32_e32 v72, v64, v56
	v_mul_f32_e32 v8, v8, v64
	v_mul_f32_e32 v10, v10, v28
	v_mul_f32_e32 v1, v1, v32
	v_mul_f32_e32 v0, v0, v38
	v_pk_add_f32 v[30:31], v[16:17], 1.0 op_sel_hi:[1,0] neg_lo:[1,0] neg_hi:[1,0]
	v_fmac_f32_e32 v73, v65, v57
	v_fmac_f32_e32 v74, v66, v58
	v_mul_f32_e32 v4, v4, v66
	v_fmac_f32_e32 v75, v67, v59
	v_fmac_f32_e32 v22, v68, v60
	v_mul_f32_e32 v2, v2, v68
	v_fmac_f32_e32 v76, v69, v61
	v_mul_f32_e32 v3, v3, v69
	v_fmac_f32_e32 v77, v70, v62
	v_fmac_f32_e32 v78, v24, v71
	v_mul_f32_e32 v6, v6, v24
	v_fmac_f32_e32 v79, v26, v72
	v_mul_f32_e32 v8, v8, v26
	v_mul_f32_e32 v16, v10, v29
	v_mul_f32_e32 v20, v1, v33
	v_mul_f32_e32 v10, v0, v39
	v_lshlrev_b32_e32 v1, 11, v47
	v_lshlrev_b32_e32 v0, 3, v48
	v_lshlrev_b32_e32 v17, 16, v9
	v_and_b32_e32 v19, 0xffff0000, v9
	v_lshlrev_b32_e32 v9, 16, v11
	v_and_b32_e32 v11, 0xffff0000, v11
	v_fmac_f32_e32 v80, v28, v73
	v_fmac_f32_e32 v81, v30, v74
	v_mul_f32_e32 v12, v4, v30
	v_fmac_f32_e32 v82, v32, v75
	v_fmac_f32_e32 v83, v34, v22
	v_mul_f32_e32 v2, v2, v34
	v_fmac_f32_e32 v84, v36, v76
	v_mul_f32_e32 v3, v3, v36
	v_fmac_f32_e32 v85, v38, v77
	v_fmac_f32_e32 v5, v25, v78
	v_mul_f32_e32 v4, v6, v25
	v_fmac_f32_e32 v7, v27, v79
	v_mul_f32_e32 v6, v8, v27
	v_add3_u32 v1, 0, v1, v0
	v_cmp_gt_i32_e32 vcc, 32, v46
	v_fmac_f32_e32 v17, v29, v80
	v_fmac_f32_e32 v19, v31, v81
	v_mul_f32_e32 v18, v12, v31
	v_fmac_f32_e32 v21, v33, v82
	v_fmac_f32_e32 v23, v35, v83
	v_mul_f32_e32 v22, v2, v35
	v_fmac_f32_e32 v9, v37, v84
	v_mul_f32_e32 v8, v3, v37
	v_fmac_f32_e32 v11, v39, v85
	ds_write_b128 v1, v[4:7]
	ds_write_b128 v1, v[16:19] offset:16
	ds_write_b128 v1, v[20:23] offset:32
	ds_write_b128 v1, v[8:11] offset:48
	s_waitcnt lgkmcnt(0)
	s_barrier
	s_waitcnt vmcnt(0)
	s_and_saveexec_b64 s[0:1], vcc
	s_cbranch_execz .LBB0_513
	v_mov_b32_e32 v2, 0
	v_mov_b32_e32 v16, 1.0
	v_add_u32_e32 v12, 0, v0
	s_mov_b32 s18, 0
	v_mov_b32_e32 v17, v16
	v_mov_b32_e32 v8, v16
	v_mov_b32_e32 v9, v16
	v_mov_b32_e32 v4, v16
	v_mov_b32_e32 v5, v16
	v_mov_b32_e32 v0, v16
	v_mov_b32_e32 v1, v16
	v_mov_b32_e32 v3, v2
	v_mov_b32_e32 v14, v2
	v_mov_b32_e32 v15, v2
	v_mov_b32_e32 v10, v2
	v_mov_b32_e32 v11, v2
	v_mov_b32_e32 v6, v2
	v_mov_b32_e32 v7, v2
.LBB0_511:
	v_add_u32_e32 v13, s18, v12
	ds_read_b128 v[18:21], v13
	ds_read_b128 v[22:25], v13 offset:16
	ds_read_b128 v[26:29], v13 offset:32
	ds_read_b128 v[30:33], v13 offset:48
	ds_read_b128 v[34:37], v13 offset:2048
	ds_read_b128 v[46:49], v13 offset:2064
	ds_read_b128 v[50:53], v13 offset:2080
	ds_read_b128 v[54:57], v13 offset:2096
	ds_read_b128 v[58:61], v13 offset:4096
	ds_read_b128 v[62:65], v13 offset:4112
	ds_read_b128 v[66:69], v13 offset:4128
	ds_read_b128 v[70:73], v13 offset:4144
	ds_read_b128 v[74:77], v13 offset:6144
	ds_read_b128 v[78:81], v13 offset:6160
	ds_read_b128 v[82:85], v13 offset:6176
	ds_read_b128 v[86:89], v13 offset:6192
	s_waitcnt lgkmcnt(14)
	v_mov_b32_e32 v38, v18
	v_mov_b32_e32 v39, v20
	v_mov_b32_e32 v20, v19
	v_mov_b32_e32 v18, v22
	v_mov_b32_e32 v19, v24
	v_mov_b32_e32 v24, v23
	s_waitcnt lgkmcnt(13)
	v_mov_b32_e32 v22, v26
	v_mov_b32_e32 v23, v28
	v_mov_b32_e32 v28, v27
	s_waitcnt lgkmcnt(12)
	v_mov_b32_e32 v26, v30
	v_mov_b32_e32 v27, v32
	v_mov_b32_e32 v32, v31
	s_waitcnt lgkmcnt(11)
	v_mov_b32_e32 v30, v34
	v_mov_b32_e32 v31, v36
	v_mov_b32_e32 v36, v35
	s_waitcnt lgkmcnt(10)
	v_mov_b32_e32 v34, v46
	v_mov_b32_e32 v35, v48
	v_mov_b32_e32 v48, v47
	s_waitcnt lgkmcnt(9)
	v_mov_b32_e32 v42, v50
	v_mov_b32_e32 v43, v52
	v_mov_b32_e32 v52, v51
	s_waitcnt lgkmcnt(8)
	v_mov_b32_e32 v46, v54
	v_mov_b32_e32 v47, v56
	v_mov_b32_e32 v56, v55
	v_pk_fma_f32 v[14:15], v[38:39], v[14:15], v[20:21]
	v_pk_mul_f32 v[8:9], v[8:9], v[38:39]
	v_pk_fma_f32 v[10:11], v[18:19], v[10:11], v[24:25]
	v_pk_mul_f32 v[4:5], v[4:5], v[18:19]
	v_pk_fma_f32 v[6:7], v[22:23], v[6:7], v[28:29]
	v_pk_mul_f32 v[0:1], v[0:1], v[22:23]
	v_pk_fma_f32 v[2:3], v[26:27], v[2:3], v[32:33]
	v_pk_mul_f32 v[16:17], v[16:17], v[26:27]
	s_waitcnt lgkmcnt(7)
	v_mov_b32_e32 v50, v58
	v_mov_b32_e32 v51, v60
	v_mov_b32_e32 v60, v59
	s_waitcnt lgkmcnt(6)
	v_mov_b32_e32 v54, v62
	v_mov_b32_e32 v55, v64
	v_mov_b32_e32 v64, v63
	s_waitcnt lgkmcnt(5)
	v_mov_b32_e32 v58, v66
	v_mov_b32_e32 v59, v68
	v_mov_b32_e32 v68, v67
	s_waitcnt lgkmcnt(4)
	v_mov_b32_e32 v62, v70
	v_mov_b32_e32 v63, v72
	v_mov_b32_e32 v72, v71
	v_pk_fma_f32 v[14:15], v[30:31], v[14:15], v[36:37]
	v_pk_mul_f32 v[8:9], v[8:9], v[30:31]
	v_pk_fma_f32 v[10:11], v[34:35], v[10:11], v[48:49]
	v_pk_mul_f32 v[4:5], v[4:5], v[34:35]
	v_pk_fma_f32 v[6:7], v[42:43], v[6:7], v[52:53]
	v_pk_mul_f32 v[0:1], v[0:1], v[42:43]
	v_pk_fma_f32 v[2:3], v[46:47], v[2:3], v[56:57]
	v_pk_mul_f32 v[16:17], v[16:17], v[46:47]
	s_addk_i32 s18, 0x2000
	s_waitcnt lgkmcnt(3)
	v_mov_b32_e32 v66, v74
	v_mov_b32_e32 v67, v76
	v_mov_b32_e32 v76, v75
	s_waitcnt lgkmcnt(2)
	v_mov_b32_e32 v70, v78
	v_mov_b32_e32 v71, v80
	v_mov_b32_e32 v80, v79
	s_waitcnt lgkmcnt(1)
	v_mov_b32_e32 v74, v82
	v_mov_b32_e32 v75, v84
	v_mov_b32_e32 v84, v83
	s_waitcnt lgkmcnt(0)
	v_mov_b32_e32 v78, v86
	v_mov_b32_e32 v79, v88
	v_mov_b32_e32 v88, v87
	v_pk_fma_f32 v[14:15], v[50:51], v[14:15], v[60:61]
	v_pk_mul_f32 v[8:9], v[8:9], v[50:51]
	v_pk_fma_f32 v[10:11], v[54:55], v[10:11], v[64:65]
	v_pk_mul_f32 v[4:5], v[4:5], v[54:55]
	v_pk_fma_f32 v[6:7], v[58:59], v[6:7], v[68:69]
	v_pk_mul_f32 v[0:1], v[0:1], v[58:59]
	v_pk_fma_f32 v[2:3], v[62:63], v[2:3], v[72:73]
	v_pk_mul_f32 v[16:17], v[16:17], v[62:63]
	s_cmpk_eq_u32 s18, 0x8000
	v_pk_fma_f32 v[14:15], v[66:67], v[14:15], v[76:77]
	v_pk_mul_f32 v[8:9], v[8:9], v[66:67]
	v_pk_fma_f32 v[10:11], v[70:71], v[10:11], v[80:81]
	v_pk_mul_f32 v[4:5], v[4:5], v[70:71]
	v_pk_fma_f32 v[6:7], v[74:75], v[6:7], v[84:85]
	v_pk_mul_f32 v[0:1], v[0:1], v[74:75]
	v_pk_fma_f32 v[2:3], v[78:79], v[2:3], v[88:89]
	v_pk_mul_f32 v[16:17], v[16:17], v[78:79]
	s_cbranch_scc0 .LBB0_511
	s_lshl_b32 s8, s33, 11
	v_lshl_or_b32 v40, v45, 1, s8
	v_lshl_add_u64 v[18:19], v[40:41], 2, s[14:15]
	v_mov_b32_e32 v12, v8
	v_mov_b32_e32 v13, v14
	v_mov_b32_e32 v14, v9
	global_store_dwordx4 v[18:19], v[12:15], off sc0 sc1
	s_nop 1
	v_lshl_add_u64 v[12:13], v[18:19], 0, 16
	v_mov_b32_e32 v8, v4
	v_mov_b32_e32 v9, v10
	v_mov_b32_e32 v10, v5
	global_store_dwordx4 v[12:13], v[8:11], off sc0 sc1
	s_nop 1
	v_lshl_add_u64 v[8:9], v[18:19], 0, 32
	v_mov_b32_e32 v4, v0
	v_mov_b32_e32 v5, v6
	v_mov_b32_e32 v6, v1
	global_store_dwordx4 v[8:9], v[4:7], off sc0 sc1
	s_nop 1
	v_lshl_add_u64 v[4:5], v[18:19], 0, 48
	v_mov_b32_e32 v0, v16
	v_mov_b32_e32 v1, v2
	v_mov_b32_e32 v2, v17
	global_store_dwordx4 v[4:5], v[0:3], off sc0 sc1
	s_nop 1
	s_nop 0
.LBB0_513:
	s_or_b64 exec, exec, s[0:1]
	v_mov_b32_e32 v46, v153
	s_barrier
	v_mov_b32_e32 v15, 0
	v_ashrrev_i32_e32 v47, 5, v46
	v_lshlrev_b32_e32 v0, 3, v46
	v_and_b32_e32 v48, 0xf8, v0
	v_lshl_add_u32 v42, v47, 2, s37
	v_or_b32_e32 v49, s36, v48
	v_ashrrev_i32_e32 v43, 31, v42
	v_or_b32_e32 v45, 0x100, v49
	v_lshlrev_b64 v[0:1], 11, v[42:43]
	v_lshl_add_u64 v[2:3], s[20:21], 0, v[0:1]
	v_lshlrev_b32_e32 v40, 1, v45
	v_lshl_add_u64 v[0:1], s[34:35], 0, v[0:1]
	v_lshl_add_u64 v[2:3], v[2:3], 0, v[40:41]
	v_lshl_add_u64 v[0:1], v[0:1], 0, v[40:41]
	v_mov_b32_e32 v36, v200
	v_mov_b32_e32 v37, v201
	v_mov_b32_e32 v38, v202
	v_mov_b32_e32 v39, v203
	v_mov_b32_e32 v32, v204
	v_mov_b32_e32 v33, v205
	v_mov_b32_e32 v34, v206
	v_mov_b32_e32 v35, v207
	v_or_b32_e32 v0, 1, v42
	v_ashrrev_i32_e32 v1, 31, v0
	v_lshlrev_b64 v[0:1], 11, v[0:1]
	v_lshl_add_u64 v[2:3], s[20:21], 0, v[0:1]
	v_lshl_add_u64 v[0:1], s[34:35], 0, v[0:1]
	v_lshl_add_u64 v[2:3], v[2:3], 0, v[40:41]
	v_lshl_add_u64 v[0:1], v[0:1], 0, v[40:41]
	v_mov_b32_e32 v28, v208
	v_mov_b32_e32 v29, v209
	v_mov_b32_e32 v30, v210
	v_mov_b32_e32 v31, v211
	v_mov_b32_e32 v20, v212
	v_mov_b32_e32 v21, v213
	v_mov_b32_e32 v22, v214
	v_mov_b32_e32 v23, v215
	v_or_b32_e32 v0, 2, v42
	v_ashrrev_i32_e32 v1, 31, v0
	v_lshlrev_b64 v[0:1], 11, v[0:1]
	v_lshl_add_u64 v[2:3], s[20:21], 0, v[0:1]
	v_lshl_add_u64 v[0:1], s[34:35], 0, v[0:1]
	v_lshl_add_u64 v[2:3], v[2:3], 0, v[40:41]
	v_lshl_add_u64 v[0:1], v[0:1], 0, v[40:41]
	v_mov_b32_e32 v4, v216
	v_mov_b32_e32 v5, v217
	v_mov_b32_e32 v6, v218
	v_mov_b32_e32 v7, v219
	v_mov_b32_e32 v24, v220
	v_mov_b32_e32 v25, v221
	v_mov_b32_e32 v26, v222
	v_mov_b32_e32 v27, v223
	v_or_b32_e32 v0, 3, v42
	v_ashrrev_i32_e32 v1, 31, v0
	v_lshlrev_b64 v[0:1], 11, v[0:1]
	v_lshl_add_u64 v[2:3], s[20:21], 0, v[0:1]
	v_lshl_add_u64 v[2:3], v[2:3], 0, v[40:41]
	v_lshl_add_u64 v[0:1], s[34:35], 0, v[0:1]
	v_lshl_add_u64 v[0:1], v[0:1], 0, v[40:41]
	v_mov_b32_e32 v16, v224
	v_mov_b32_e32 v17, v225
	v_mov_b32_e32 v18, v226
	v_mov_b32_e32 v19, v227
	v_mov_b32_e32 v8, v228
	v_mov_b32_e32 v9, v229
	v_mov_b32_e32 v10, v230
	v_mov_b32_e32 v11, v231
	v_cmp_lt_i32_e32 vcc, s27, v42
	v_mov_b32_e32 v3, 0
	v_mov_b32_e32 v2, 0
	v_mov_b32_e32 v1, 0
	v_mov_b32_e32 v0, 0
	v_mov_b32_e32 v14, 0
	v_mov_b32_e32 v13, 0
	v_mov_b32_e32 v12, 0
	s_and_saveexec_b64 s[0:1], vcc
	s_cbranch_execz .LBB0_515
	v_add_u32_e32 v0, 0xffffbf80, v42
	v_lshrrev_b32_e32 v40, 2, v0
	v_lshlrev_b64 v[0:1], 12, v[40:41]
	v_lshl_add_u64 v[0:1], s[58:59], 0, v[0:1]
	v_lshlrev_b32_e32 v40, 2, v49
	v_lshl_add_u64 v[0:1], v[0:1], 0, v[40:41]
	global_load_dwordx4 v[12:15], v[0:1], off offset:1024
	s_nop 0
	global_load_dwordx4 v[0:3], v[0:1], off offset:1040
